# x-projection GEMM main loop: pointer stepping and next-iteration pointer selection issued behind the MFMAs of the last compute segment instead of ahead of the first load segment
# speedup vs baseline: 1.0215x; 1.0177x over previous
.LBB0_630:
	s_ashr_i32 s85, s84, 31
	s_lshl_b64 s[22:23], s[84:85], 20
	s_cmp_eq_u32 s52, 0
	v_mov_b64_e32 v[0:1], 0x3a0
	s_cselect_b32 s31, s14, s50
	v_cmp_lt_i64_e32 vcc, s[76:77], v[0:1]
	s_cselect_b32 s30, s15, s51
	s_cselect_b32 s38, s8, s14
	s_cselect_b32 s39, s9, s15
	s_add_u32 s76, s31, s22
	s_addc_u32 s77, s30, s23
	s_and_b64 s[22:23], vcc, exec
	s_cselect_b32 s30, s77, s89
	s_cselect_b32 s31, s76, s88
	s_ashr_i32 s83, s82, 31
	s_lshl_b64 s[22:23], s[82:83], 20
	s_add_u32 s86, s38, s22
	s_addc_u32 s87, s39, s23
	s_and_b64 s[22:23], vcc, exec
	s_cselect_b32 s38, s87, s91
	s_cselect_b32 s39, s86, s90
	s_add_u32 s88, s88, 0x80080
	s_addc_u32 s89, s89, 0
	s_add_u32 s41, s90, 0x100
	s_addc_u32 s42, s91, 0
	s_mov_b32 s43, -2
	s_add_u32 s22, s88, 0xfff80080
	s_addc_u32 s23, s89, -1
	s_add_u32 s44, s88, 0xfff80000
	s_addc_u32 s45, s89, -1
	s_cmp_eq_u32 s43, 28
	s_cselect_b32 s23, s30, s23
	s_cselect_b32 s22, s31, s22
	s_cselect_b32 s91, s38, s42
	s_cselect_b32 s90, s39, s41
	s_add_i32 s81, 0, 0x14000
	ds_read_b128 v[144:147], v222
	ds_read_b128 v[148:151], v222 offset:1024
	ds_read_b128 v[152:155], v222 offset:2048
	ds_read_b128 v[156:159], v222 offset:3072
	ds_read_b128 v[160:163], v223
	ds_read_b128 v[164:167], v223 offset:1024
	ds_read_b128 v[168:171], v223 offset:2048
	ds_read_b128 v[172:175], v223 offset:3072
	s_mov_b32 m0, s92
	ds_read_b128 v[176:179], v143
	ds_read_b128 v[180:183], v143 offset:1024
	ds_read_b128 v[184:187], v143 offset:2048
	ds_read_b128 v[188:191], v143 offset:3072
	ds_read_b128 v[192:195], v143 offset:4096
	ds_read_b128 v[196:199], v143 offset:5120
	ds_read_b128 v[200:203], v143 offset:6144
	ds_read_b128 v[204:207], v143 offset:7168
	global_load_lds_dwordx4 v128, s[44:45]
	s_mov_b32 m0, s6
	s_nop 0
	global_load_lds_dwordx4 v132, s[44:45]
	s_add_i32 m0, s57, 0xc000
	s_nop 0
	global_load_lds_dwordx4 v136, s[88:89]
	s_add_i32 m0, s57, 0xe000
	s_nop 0
	global_load_lds_dwordx4 v138, s[88:89]
	s_waitcnt vmcnt(8)
	s_waitcnt lgkmcnt(0)
	s_barrier
	v_mfma_f32_16x16x32_bf16 v[124:127], v[144:147], v[176:179], 0
	v_mfma_f32_16x16x32_bf16 v[120:123], v[152:155], v[176:179], 0
	v_mfma_f32_16x16x32_bf16 v[116:119], v[144:147], v[184:187], 0
	v_mfma_f32_16x16x32_bf16 v[112:115], v[152:155], v[184:187], 0
	v_mfma_f32_16x16x32_bf16 v[100:103], v[144:147], v[192:195], 0
	v_mfma_f32_16x16x32_bf16 v[96:99], v[152:155], v[192:195], 0
	v_mfma_f32_16x16x32_bf16 v[84:87], v[144:147], v[200:203], 0
	v_mfma_f32_16x16x32_bf16 v[80:83], v[152:155], v[200:203], 0
	v_mfma_f32_16x16x32_bf16 v[124:127], v[148:151], v[180:183], v[124:127]
	v_mfma_f32_16x16x32_bf16 v[120:123], v[156:159], v[180:183], v[120:123]
	v_mfma_f32_16x16x32_bf16 v[116:119], v[148:151], v[188:191], v[116:119]
	v_mfma_f32_16x16x32_bf16 v[112:115], v[156:159], v[188:191], v[112:115]
	v_mfma_f32_16x16x32_bf16 v[100:103], v[148:151], v[196:199], v[100:103]
	v_mfma_f32_16x16x32_bf16 v[96:99], v[156:159], v[196:199], v[96:99]
	v_mfma_f32_16x16x32_bf16 v[84:87], v[148:151], v[204:207], v[84:87]
	v_mfma_f32_16x16x32_bf16 v[80:83], v[156:159], v[204:207], v[80:83]
	v_mfma_f32_16x16x32_bf16 v[108:111], v[160:163], v[176:179], 0
	v_mfma_f32_16x16x32_bf16 v[104:107], v[168:171], v[176:179], 0
	v_mfma_f32_16x16x32_bf16 v[92:95], v[160:163], v[184:187], 0
	v_mfma_f32_16x16x32_bf16 v[88:91], v[168:171], v[184:187], 0
	v_mfma_f32_16x16x32_bf16 v[76:79], v[160:163], v[192:195], 0
	v_mfma_f32_16x16x32_bf16 v[72:75], v[168:171], v[192:195], 0
	v_mfma_f32_16x16x32_bf16 v[68:71], v[160:163], v[200:203], 0
	v_mfma_f32_16x16x32_bf16 v[64:67], v[168:171], v[200:203], 0
	v_mfma_f32_16x16x32_bf16 v[108:111], v[164:167], v[180:183], v[108:111]
	v_mfma_f32_16x16x32_bf16 v[104:107], v[172:175], v[180:183], v[104:107]
	v_mfma_f32_16x16x32_bf16 v[92:95], v[164:167], v[188:191], v[92:95]
	v_mfma_f32_16x16x32_bf16 v[88:91], v[172:175], v[188:191], v[88:91]
	v_mfma_f32_16x16x32_bf16 v[76:79], v[164:167], v[196:199], v[76:79]
	v_mfma_f32_16x16x32_bf16 v[72:75], v[172:175], v[196:199], v[72:75]
	v_mfma_f32_16x16x32_bf16 v[68:71], v[164:167], v[204:207], v[68:71]
	v_mfma_f32_16x16x32_bf16 v[64:67], v[172:175], v[204:207], v[64:67]
	s_barrier
	s_add_i32 s44, s96, 0x10000
	s_mov_b32 m0, s44
	ds_read_b128 v[176:179], v143 offset:16384
	ds_read_b128 v[180:183], v143 offset:17408
	ds_read_b128 v[184:187], v143 offset:18432
	ds_read_b128 v[188:191], v143 offset:19456
	ds_read_b128 v[192:195], v143 offset:20480
	ds_read_b128 v[196:199], v143 offset:21504
	ds_read_b128 v[200:203], v143 offset:22528
	ds_read_b128 v[204:207], v143 offset:23552
	global_load_lds_dwordx4 v130, s[90:91]
	s_add_i32 m0, s44, 0x2000
	s_add_u32 s44, s90, 0x80000
	s_addc_u32 s45, s91, 0
	s_add_i32 s81, s81, s96
	global_load_lds_dwordx4 v134, s[90:91]
	s_mov_b32 m0, s81
	s_nop 0
	global_load_lds_dwordx4 v130, s[44:45]
	s_add_i32 m0, s81, 0x2000
	s_nop 0
	global_load_lds_dwordx4 v134, s[44:45]
	s_waitcnt vmcnt(6)
	s_waitcnt lgkmcnt(0)
	s_barrier
	v_mfma_f32_16x16x32_bf16 v[60:63], v[144:147], v[176:179], 0
	v_mfma_f32_16x16x32_bf16 v[56:59], v[152:155], v[176:179], 0
	v_mfma_f32_16x16x32_bf16 v[52:55], v[144:147], v[184:187], 0
	v_mfma_f32_16x16x32_bf16 v[48:51], v[152:155], v[184:187], 0
	v_mfma_f32_16x16x32_bf16 v[36:39], v[144:147], v[192:195], 0
	v_mfma_f32_16x16x32_bf16 v[32:35], v[152:155], v[192:195], 0
	v_mfma_f32_16x16x32_bf16 v[20:23], v[144:147], v[200:203], 0
	v_mfma_f32_16x16x32_bf16 v[16:19], v[152:155], v[200:203], 0
	v_mfma_f32_16x16x32_bf16 v[60:63], v[148:151], v[180:183], v[60:63]
	v_mfma_f32_16x16x32_bf16 v[56:59], v[156:159], v[180:183], v[56:59]
	v_mfma_f32_16x16x32_bf16 v[52:55], v[148:151], v[188:191], v[52:55]
	v_mfma_f32_16x16x32_bf16 v[48:51], v[156:159], v[188:191], v[48:51]
	v_mfma_f32_16x16x32_bf16 v[36:39], v[148:151], v[196:199], v[36:39]
	v_mfma_f32_16x16x32_bf16 v[32:35], v[156:159], v[196:199], v[32:35]
	v_mfma_f32_16x16x32_bf16 v[20:23], v[148:151], v[204:207], v[20:23]
	v_mfma_f32_16x16x32_bf16 v[16:19], v[156:159], v[204:207], v[16:19]
	v_mfma_f32_16x16x32_bf16 v[44:47], v[160:163], v[176:179], 0
	v_mfma_f32_16x16x32_bf16 v[40:43], v[168:171], v[176:179], 0
	v_mfma_f32_16x16x32_bf16 v[28:31], v[160:163], v[184:187], 0
	v_mfma_f32_16x16x32_bf16 v[24:27], v[168:171], v[184:187], 0
	v_mfma_f32_16x16x32_bf16 v[12:15], v[160:163], v[192:195], 0
	v_mfma_f32_16x16x32_bf16 v[8:11], v[168:171], v[192:195], 0
	v_mfma_f32_16x16x32_bf16 v[4:7], v[160:163], v[200:203], 0
	v_mfma_f32_16x16x32_bf16 v[0:3], v[168:171], v[200:203], 0
	v_mfma_f32_16x16x32_bf16 v[44:47], v[164:167], v[180:183], v[44:47]
	v_mfma_f32_16x16x32_bf16 v[40:43], v[172:175], v[180:183], v[40:43]
	v_mfma_f32_16x16x32_bf16 v[28:31], v[164:167], v[188:191], v[28:31]
	v_mfma_f32_16x16x32_bf16 v[24:27], v[172:175], v[188:191], v[24:27]
	v_mfma_f32_16x16x32_bf16 v[12:15], v[164:167], v[196:199], v[12:15]
	v_mfma_f32_16x16x32_bf16 v[8:11], v[172:175], v[196:199], v[8:11]
	v_mfma_f32_16x16x32_bf16 v[4:7], v[164:167], v[204:207], v[4:7]
	v_mfma_f32_16x16x32_bf16 v[0:3], v[172:175], v[204:207], v[0:3]
	s_barrier
	s_add_i32 s44, 0, 0x18000
	s_add_i32 s45, 0, 0x1c000
	ds_read_b128 v[144:147], v224
	ds_read_b128 v[148:151], v224 offset:1024
	ds_read_b128 v[152:155], v224 offset:2048
	ds_read_b128 v[156:159], v224 offset:3072
	ds_read_b128 v[160:163], v225
	ds_read_b128 v[164:167], v225 offset:1024
	ds_read_b128 v[168:171], v225 offset:2048
	ds_read_b128 v[172:175], v225 offset:3072
	ds_read_b128 v[176:179], v143 offset:32768
	ds_read_b128 v[180:183], v143 offset:33792
	ds_read_b128 v[184:187], v143 offset:34816
	ds_read_b128 v[188:191], v143 offset:35840
	ds_read_b128 v[192:195], v143 offset:36864
	ds_read_b128 v[196:199], v143 offset:37888
	ds_read_b128 v[200:203], v143 offset:38912
	ds_read_b128 v[204:207], v143 offset:39936
	s_mov_b32 m0, s57
	s_nop 0
	global_load_lds_dwordx4 v128, s[22:23]
	s_mov_b32 m0, s97
	s_nop 0
	global_load_lds_dwordx4 v132, s[22:23]
	s_mov_b32 m0, s93
	s_add_u32 s22, s22, 0x80000
	s_addc_u32 s23, s23, 0
	global_load_lds_dwordx4 v128, s[22:23]
	s_mov_b32 m0, s94
	s_nop 0
	global_load_lds_dwordx4 v132, s[22:23]
	s_waitcnt vmcnt(8)
	s_waitcnt lgkmcnt(0)
	s_barrier
	v_mfma_f32_16x16x32_bf16 v[124:127], v[144:147], v[176:179], v[124:127]
	v_mfma_f32_16x16x32_bf16 v[120:123], v[152:155], v[176:179], v[120:123]
	v_mfma_f32_16x16x32_bf16 v[116:119], v[144:147], v[184:187], v[116:119]
	v_mfma_f32_16x16x32_bf16 v[112:115], v[152:155], v[184:187], v[112:115]
	v_mfma_f32_16x16x32_bf16 v[100:103], v[144:147], v[192:195], v[100:103]
	v_mfma_f32_16x16x32_bf16 v[96:99], v[152:155], v[192:195], v[96:99]
	v_mfma_f32_16x16x32_bf16 v[84:87], v[144:147], v[200:203], v[84:87]
	v_mfma_f32_16x16x32_bf16 v[80:83], v[152:155], v[200:203], v[80:83]
	v_mfma_f32_16x16x32_bf16 v[124:127], v[148:151], v[180:183], v[124:127]
	v_mfma_f32_16x16x32_bf16 v[120:123], v[156:159], v[180:183], v[120:123]
	v_mfma_f32_16x16x32_bf16 v[116:119], v[148:151], v[188:191], v[116:119]
	v_mfma_f32_16x16x32_bf16 v[112:115], v[156:159], v[188:191], v[112:115]
	v_mfma_f32_16x16x32_bf16 v[100:103], v[148:151], v[196:199], v[100:103]
	v_mfma_f32_16x16x32_bf16 v[96:99], v[156:159], v[196:199], v[96:99]
	v_mfma_f32_16x16x32_bf16 v[84:87], v[148:151], v[204:207], v[84:87]
	v_mfma_f32_16x16x32_bf16 v[80:83], v[156:159], v[204:207], v[80:83]
	v_mfma_f32_16x16x32_bf16 v[108:111], v[160:163], v[176:179], v[108:111]
	v_mfma_f32_16x16x32_bf16 v[104:107], v[168:171], v[176:179], v[104:107]
	v_mfma_f32_16x16x32_bf16 v[92:95], v[160:163], v[184:187], v[92:95]
	v_mfma_f32_16x16x32_bf16 v[88:91], v[168:171], v[184:187], v[88:91]
	v_mfma_f32_16x16x32_bf16 v[76:79], v[160:163], v[192:195], v[76:79]
	v_mfma_f32_16x16x32_bf16 v[72:75], v[168:171], v[192:195], v[72:75]
	v_mfma_f32_16x16x32_bf16 v[68:71], v[160:163], v[200:203], v[68:71]
	v_mfma_f32_16x16x32_bf16 v[64:67], v[168:171], v[200:203], v[64:67]
	v_mfma_f32_16x16x32_bf16 v[108:111], v[164:167], v[180:183], v[108:111]
	v_mfma_f32_16x16x32_bf16 v[104:107], v[172:175], v[180:183], v[104:107]
	v_mfma_f32_16x16x32_bf16 v[92:95], v[164:167], v[188:191], v[92:95]
	v_mfma_f32_16x16x32_bf16 v[88:91], v[172:175], v[188:191], v[88:91]
	v_mfma_f32_16x16x32_bf16 v[76:79], v[164:167], v[196:199], v[76:79]
	v_mfma_f32_16x16x32_bf16 v[72:75], v[172:175], v[196:199], v[72:75]
	v_mfma_f32_16x16x32_bf16 v[68:71], v[164:167], v[204:207], v[68:71]
	v_mfma_f32_16x16x32_bf16 v[64:67], v[172:175], v[204:207], v[64:67]
	s_barrier
	s_add_i32 s22, s44, s96
	s_add_i32 m0, s22, 0xffffff80
	ds_read_b128 v[176:179], v143 offset:49152
	ds_read_b128 v[180:183], v143 offset:50176
	ds_read_b128 v[184:187], v143 offset:51200
	ds_read_b128 v[188:191], v143 offset:52224
	ds_read_b128 v[192:195], v143 offset:53248
	ds_read_b128 v[196:199], v143 offset:54272
	ds_read_b128 v[200:203], v143 offset:55296
	ds_read_b128 v[204:207], v143 offset:56320
	global_load_lds_dwordx4 v130, s[90:91] offset:128
	s_add_i32 m0, s22, 0x1f80
	s_add_u32 s22, s90, 0x80080
	s_addc_u32 s23, s91, 0
	s_add_i32 s44, s45, s96
	global_load_lds_dwordx4 v134, s[90:91] offset:128
	s_mov_b32 m0, s44
	s_nop 0
	global_load_lds_dwordx4 v130, s[22:23]
	s_add_i32 m0, s44, 0x2000
	s_nop 0
	global_load_lds_dwordx4 v134, s[22:23]
	s_waitcnt vmcnt(6)
	s_waitcnt lgkmcnt(0)
	s_barrier
	v_mfma_f32_16x16x32_bf16 v[60:63], v[144:147], v[176:179], v[60:63]
	v_mfma_f32_16x16x32_bf16 v[56:59], v[152:155], v[176:179], v[56:59]
	s_add_i32 s43, s43, 2
	v_mfma_f32_16x16x32_bf16 v[52:55], v[144:147], v[184:187], v[52:55]
	s_add_u32 s88, s88, 0x100
	s_addc_u32 s89, s89, 0
	v_mfma_f32_16x16x32_bf16 v[48:51], v[152:155], v[184:187], v[48:51]
	s_add_u32 s41, s41, 0x100
	s_addc_u32 s42, s42, 0
	v_mfma_f32_16x16x32_bf16 v[36:39], v[144:147], v[192:195], v[36:39]
	s_add_u32 s22, s88, 0xfff80080
	s_addc_u32 s23, s89, -1
	v_mfma_f32_16x16x32_bf16 v[32:35], v[152:155], v[192:195], v[32:35]
	s_add_u32 s44, s88, 0xfff80000
	s_addc_u32 s45, s89, -1
	v_mfma_f32_16x16x32_bf16 v[20:23], v[144:147], v[200:203], v[20:23]
	s_cmp_eq_u32 s43, 28
	s_cselect_b32 s23, s30, s23
	s_cselect_b32 s22, s31, s22
	s_cselect_b32 s91, s38, s42
	s_cselect_b32 s90, s39, s41
	v_mfma_f32_16x16x32_bf16 v[16:19], v[152:155], v[200:203], v[16:19]
	s_add_i32 s81, 0, 0x14000
	v_mfma_f32_16x16x32_bf16 v[60:63], v[148:151], v[180:183], v[60:63]
	v_mfma_f32_16x16x32_bf16 v[56:59], v[156:159], v[180:183], v[56:59]
	v_mfma_f32_16x16x32_bf16 v[52:55], v[148:151], v[188:191], v[52:55]
	v_mfma_f32_16x16x32_bf16 v[48:51], v[156:159], v[188:191], v[48:51]
	v_mfma_f32_16x16x32_bf16 v[36:39], v[148:151], v[196:199], v[36:39]
	v_mfma_f32_16x16x32_bf16 v[32:35], v[156:159], v[196:199], v[32:35]
	v_mfma_f32_16x16x32_bf16 v[20:23], v[148:151], v[204:207], v[20:23]
	v_mfma_f32_16x16x32_bf16 v[16:19], v[156:159], v[204:207], v[16:19]
	v_mfma_f32_16x16x32_bf16 v[44:47], v[160:163], v[176:179], v[44:47]
	v_mfma_f32_16x16x32_bf16 v[40:43], v[168:171], v[176:179], v[40:43]
	v_mfma_f32_16x16x32_bf16 v[28:31], v[160:163], v[184:187], v[28:31]
	v_mfma_f32_16x16x32_bf16 v[24:27], v[168:171], v[184:187], v[24:27]
	v_mfma_f32_16x16x32_bf16 v[12:15], v[160:163], v[192:195], v[12:15]
	v_mfma_f32_16x16x32_bf16 v[8:11], v[168:171], v[192:195], v[8:11]
	v_mfma_f32_16x16x32_bf16 v[4:7], v[160:163], v[200:203], v[4:7]
	v_mfma_f32_16x16x32_bf16 v[0:3], v[168:171], v[200:203], v[0:3]
	v_mfma_f32_16x16x32_bf16 v[44:47], v[164:167], v[180:183], v[44:47]
	v_mfma_f32_16x16x32_bf16 v[40:43], v[172:175], v[180:183], v[40:43]
	v_mfma_f32_16x16x32_bf16 v[28:31], v[164:167], v[188:191], v[28:31]
	v_mfma_f32_16x16x32_bf16 v[24:27], v[172:175], v[188:191], v[24:27]
	v_mfma_f32_16x16x32_bf16 v[12:15], v[164:167], v[196:199], v[12:15]
	v_mfma_f32_16x16x32_bf16 v[8:11], v[172:175], v[196:199], v[8:11]
	v_mfma_f32_16x16x32_bf16 v[4:7], v[164:167], v[204:207], v[4:7]
	v_mfma_f32_16x16x32_bf16 v[0:3], v[172:175], v[204:207], v[0:3]
	s_barrier
	s_cmp_gt_u32 s43, 29
	s_cbranch_scc0 .LBB0_631
.LBB0_631:
	ds_read_b128 v[144:147], v222
	ds_read_b128 v[148:151], v222 offset:1024
	ds_read_b128 v[152:155], v222 offset:2048
	ds_read_b128 v[156:159], v222 offset:3072
	ds_read_b128 v[160:163], v223
	ds_read_b128 v[164:167], v223 offset:1024
	ds_read_b128 v[168:171], v223 offset:2048
	ds_read_b128 v[172:175], v223 offset:3072
	s_mov_b32 m0, s92
	ds_read_b128 v[176:179], v143
	ds_read_b128 v[180:183], v143 offset:1024
	ds_read_b128 v[184:187], v143 offset:2048
	ds_read_b128 v[188:191], v143 offset:3072
	ds_read_b128 v[192:195], v143 offset:4096
	ds_read_b128 v[196:199], v143 offset:5120
	ds_read_b128 v[200:203], v143 offset:6144
	ds_read_b128 v[204:207], v143 offset:7168
	global_load_lds_dwordx4 v128, s[44:45]
	s_mov_b32 m0, s6
	s_nop 0
	global_load_lds_dwordx4 v132, s[44:45]
	s_add_i32 m0, s57, 0xc000
	s_nop 0
	global_load_lds_dwordx4 v136, s[88:89]
	s_add_i32 m0, s57, 0xe000
	s_nop 0
	global_load_lds_dwordx4 v138, s[88:89]
	s_waitcnt vmcnt(8)
	s_waitcnt lgkmcnt(0)
	s_barrier
	v_mfma_f32_16x16x32_bf16 v[124:127], v[144:147], v[176:179], v[124:127]
	v_mfma_f32_16x16x32_bf16 v[120:123], v[152:155], v[176:179], v[120:123]
	v_mfma_f32_16x16x32_bf16 v[116:119], v[144:147], v[184:187], v[116:119]
	v_mfma_f32_16x16x32_bf16 v[112:115], v[152:155], v[184:187], v[112:115]
	v_mfma_f32_16x16x32_bf16 v[100:103], v[144:147], v[192:195], v[100:103]
	v_mfma_f32_16x16x32_bf16 v[96:99], v[152:155], v[192:195], v[96:99]
	v_mfma_f32_16x16x32_bf16 v[84:87], v[144:147], v[200:203], v[84:87]
	v_mfma_f32_16x16x32_bf16 v[80:83], v[152:155], v[200:203], v[80:83]
	v_mfma_f32_16x16x32_bf16 v[124:127], v[148:151], v[180:183], v[124:127]
	v_mfma_f32_16x16x32_bf16 v[120:123], v[156:159], v[180:183], v[120:123]
	v_mfma_f32_16x16x32_bf16 v[116:119], v[148:151], v[188:191], v[116:119]
	v_mfma_f32_16x16x32_bf16 v[112:115], v[156:159], v[188:191], v[112:115]
	v_mfma_f32_16x16x32_bf16 v[100:103], v[148:151], v[196:199], v[100:103]
	v_mfma_f32_16x16x32_bf16 v[96:99], v[156:159], v[196:199], v[96:99]
	v_mfma_f32_16x16x32_bf16 v[84:87], v[148:151], v[204:207], v[84:87]
	v_mfma_f32_16x16x32_bf16 v[80:83], v[156:159], v[204:207], v[80:83]
	v_mfma_f32_16x16x32_bf16 v[108:111], v[160:163], v[176:179], v[108:111]
	v_mfma_f32_16x16x32_bf16 v[104:107], v[168:171], v[176:179], v[104:107]
	v_mfma_f32_16x16x32_bf16 v[92:95], v[160:163], v[184:187], v[92:95]
	v_mfma_f32_16x16x32_bf16 v[88:91], v[168:171], v[184:187], v[88:91]
	v_mfma_f32_16x16x32_bf16 v[76:79], v[160:163], v[192:195], v[76:79]
	v_mfma_f32_16x16x32_bf16 v[72:75], v[168:171], v[192:195], v[72:75]
	v_mfma_f32_16x16x32_bf16 v[68:71], v[160:163], v[200:203], v[68:71]
	v_mfma_f32_16x16x32_bf16 v[64:67], v[168:171], v[200:203], v[64:67]
	v_mfma_f32_16x16x32_bf16 v[108:111], v[164:167], v[180:183], v[108:111]
	v_mfma_f32_16x16x32_bf16 v[104:107], v[172:175], v[180:183], v[104:107]
	v_mfma_f32_16x16x32_bf16 v[92:95], v[164:167], v[188:191], v[92:95]
	v_mfma_f32_16x16x32_bf16 v[88:91], v[172:175], v[188:191], v[88:91]
	v_mfma_f32_16x16x32_bf16 v[76:79], v[164:167], v[196:199], v[76:79]
	v_mfma_f32_16x16x32_bf16 v[72:75], v[172:175], v[196:199], v[72:75]
	v_mfma_f32_16x16x32_bf16 v[68:71], v[164:167], v[204:207], v[68:71]
	v_mfma_f32_16x16x32_bf16 v[64:67], v[172:175], v[204:207], v[64:67]
	s_barrier
	s_add_i32 s44, s96, 0x10000
	s_mov_b32 m0, s44
	ds_read_b128 v[176:179], v143 offset:16384
	ds_read_b128 v[180:183], v143 offset:17408
	ds_read_b128 v[184:187], v143 offset:18432
	ds_read_b128 v[188:191], v143 offset:19456
	ds_read_b128 v[192:195], v143 offset:20480
	ds_read_b128 v[196:199], v143 offset:21504
	ds_read_b128 v[200:203], v143 offset:22528
	ds_read_b128 v[204:207], v143 offset:23552
	global_load_lds_dwordx4 v130, s[90:91]
	s_add_i32 m0, s44, 0x2000
	s_add_u32 s44, s90, 0x80000
	s_addc_u32 s45, s91, 0
	s_add_i32 s81, s81, s96
	global_load_lds_dwordx4 v134, s[90:91]
	s_mov_b32 m0, s81
	s_nop 0
	global_load_lds_dwordx4 v130, s[44:45]
	s_add_i32 m0, s81, 0x2000
	s_nop 0
	global_load_lds_dwordx4 v134, s[44:45]
	s_waitcnt vmcnt(6)
	s_waitcnt lgkmcnt(0)
	s_barrier
	v_mfma_f32_16x16x32_bf16 v[60:63], v[144:147], v[176:179], v[60:63]
	v_mfma_f32_16x16x32_bf16 v[56:59], v[152:155], v[176:179], v[56:59]
	v_mfma_f32_16x16x32_bf16 v[52:55], v[144:147], v[184:187], v[52:55]
	v_mfma_f32_16x16x32_bf16 v[48:51], v[152:155], v[184:187], v[48:51]
	v_mfma_f32_16x16x32_bf16 v[36:39], v[144:147], v[192:195], v[36:39]
	v_mfma_f32_16x16x32_bf16 v[32:35], v[152:155], v[192:195], v[32:35]
	v_mfma_f32_16x16x32_bf16 v[20:23], v[144:147], v[200:203], v[20:23]
	v_mfma_f32_16x16x32_bf16 v[16:19], v[152:155], v[200:203], v[16:19]
	v_mfma_f32_16x16x32_bf16 v[60:63], v[148:151], v[180:183], v[60:63]
	v_mfma_f32_16x16x32_bf16 v[56:59], v[156:159], v[180:183], v[56:59]
	v_mfma_f32_16x16x32_bf16 v[52:55], v[148:151], v[188:191], v[52:55]
	v_mfma_f32_16x16x32_bf16 v[48:51], v[156:159], v[188:191], v[48:51]
	v_mfma_f32_16x16x32_bf16 v[36:39], v[148:151], v[196:199], v[36:39]
	v_mfma_f32_16x16x32_bf16 v[32:35], v[156:159], v[196:199], v[32:35]
	v_mfma_f32_16x16x32_bf16 v[20:23], v[148:151], v[204:207], v[20:23]
	v_mfma_f32_16x16x32_bf16 v[16:19], v[156:159], v[204:207], v[16:19]
	v_mfma_f32_16x16x32_bf16 v[44:47], v[160:163], v[176:179], v[44:47]
	v_mfma_f32_16x16x32_bf16 v[40:43], v[168:171], v[176:179], v[40:43]
	v_mfma_f32_16x16x32_bf16 v[28:31], v[160:163], v[184:187], v[28:31]
	v_mfma_f32_16x16x32_bf16 v[24:27], v[168:171], v[184:187], v[24:27]
	v_mfma_f32_16x16x32_bf16 v[12:15], v[160:163], v[192:195], v[12:15]
	v_mfma_f32_16x16x32_bf16 v[8:11], v[168:171], v[192:195], v[8:11]
	v_mfma_f32_16x16x32_bf16 v[4:7], v[160:163], v[200:203], v[4:7]
	v_mfma_f32_16x16x32_bf16 v[0:3], v[168:171], v[200:203], v[0:3]
	v_mfma_f32_16x16x32_bf16 v[44:47], v[164:167], v[180:183], v[44:47]
	v_mfma_f32_16x16x32_bf16 v[40:43], v[172:175], v[180:183], v[40:43]
	v_mfma_f32_16x16x32_bf16 v[28:31], v[164:167], v[188:191], v[28:31]
	v_mfma_f32_16x16x32_bf16 v[24:27], v[172:175], v[188:191], v[24:27]
	v_mfma_f32_16x16x32_bf16 v[12:15], v[164:167], v[196:199], v[12:15]
	v_mfma_f32_16x16x32_bf16 v[8:11], v[172:175], v[196:199], v[8:11]
	v_mfma_f32_16x16x32_bf16 v[4:7], v[164:167], v[204:207], v[4:7]
	v_mfma_f32_16x16x32_bf16 v[0:3], v[172:175], v[204:207], v[0:3]
	s_barrier
	s_add_i32 s44, 0, 0x18000
	s_add_i32 s45, 0, 0x1c000
	ds_read_b128 v[144:147], v224
	ds_read_b128 v[148:151], v224 offset:1024
	ds_read_b128 v[152:155], v224 offset:2048
	ds_read_b128 v[156:159], v224 offset:3072
	ds_read_b128 v[160:163], v225
	ds_read_b128 v[164:167], v225 offset:1024
	ds_read_b128 v[168:171], v225 offset:2048
	ds_read_b128 v[172:175], v225 offset:3072
	ds_read_b128 v[176:179], v143 offset:32768
	ds_read_b128 v[180:183], v143 offset:33792
	ds_read_b128 v[184:187], v143 offset:34816
	ds_read_b128 v[188:191], v143 offset:35840
	ds_read_b128 v[192:195], v143 offset:36864
	ds_read_b128 v[196:199], v143 offset:37888
	ds_read_b128 v[200:203], v143 offset:38912
	ds_read_b128 v[204:207], v143 offset:39936
	s_mov_b32 m0, s57
	s_nop 0
	global_load_lds_dwordx4 v128, s[22:23]
	s_mov_b32 m0, s97
	s_nop 0
	global_load_lds_dwordx4 v132, s[22:23]
	s_mov_b32 m0, s93
	s_add_u32 s22, s22, 0x80000
	s_addc_u32 s23, s23, 0
	global_load_lds_dwordx4 v128, s[22:23]
	s_mov_b32 m0, s94
	s_nop 0
	global_load_lds_dwordx4 v132, s[22:23]
	s_waitcnt vmcnt(8)
	s_waitcnt lgkmcnt(0)
	s_barrier
	v_mfma_f32_16x16x32_bf16 v[124:127], v[144:147], v[176:179], v[124:127]
	v_mfma_f32_16x16x32_bf16 v[120:123], v[152:155], v[176:179], v[120:123]
	v_mfma_f32_16x16x32_bf16 v[116:119], v[144:147], v[184:187], v[116:119]
	v_mfma_f32_16x16x32_bf16 v[112:115], v[152:155], v[184:187], v[112:115]
	v_mfma_f32_16x16x32_bf16 v[100:103], v[144:147], v[192:195], v[100:103]
	v_mfma_f32_16x16x32_bf16 v[96:99], v[152:155], v[192:195], v[96:99]
	v_mfma_f32_16x16x32_bf16 v[84:87], v[144:147], v[200:203], v[84:87]
	v_mfma_f32_16x16x32_bf16 v[80:83], v[152:155], v[200:203], v[80:83]
	v_mfma_f32_16x16x32_bf16 v[124:127], v[148:151], v[180:183], v[124:127]
	v_mfma_f32_16x16x32_bf16 v[120:123], v[156:159], v[180:183], v[120:123]
	v_mfma_f32_16x16x32_bf16 v[116:119], v[148:151], v[188:191], v[116:119]
	v_mfma_f32_16x16x32_bf16 v[112:115], v[156:159], v[188:191], v[112:115]
	v_mfma_f32_16x16x32_bf16 v[100:103], v[148:151], v[196:199], v[100:103]
	v_mfma_f32_16x16x32_bf16 v[96:99], v[156:159], v[196:199], v[96:99]
	v_mfma_f32_16x16x32_bf16 v[84:87], v[148:151], v[204:207], v[84:87]
	v_mfma_f32_16x16x32_bf16 v[80:83], v[156:159], v[204:207], v[80:83]
	v_mfma_f32_16x16x32_bf16 v[108:111], v[160:163], v[176:179], v[108:111]
	v_mfma_f32_16x16x32_bf16 v[104:107], v[168:171], v[176:179], v[104:107]
	v_mfma_f32_16x16x32_bf16 v[92:95], v[160:163], v[184:187], v[92:95]
	v_mfma_f32_16x16x32_bf16 v[88:91], v[168:171], v[184:187], v[88:91]
	v_mfma_f32_16x16x32_bf16 v[76:79], v[160:163], v[192:195], v[76:79]
	v_mfma_f32_16x16x32_bf16 v[72:75], v[168:171], v[192:195], v[72:75]
	v_mfma_f32_16x16x32_bf16 v[68:71], v[160:163], v[200:203], v[68:71]
	v_mfma_f32_16x16x32_bf16 v[64:67], v[168:171], v[200:203], v[64:67]
	v_mfma_f32_16x16x32_bf16 v[108:111], v[164:167], v[180:183], v[108:111]
	v_mfma_f32_16x16x32_bf16 v[104:107], v[172:175], v[180:183], v[104:107]
	v_mfma_f32_16x16x32_bf16 v[92:95], v[164:167], v[188:191], v[92:95]
	v_mfma_f32_16x16x32_bf16 v[88:91], v[172:175], v[188:191], v[88:91]
	v_mfma_f32_16x16x32_bf16 v[76:79], v[164:167], v[196:199], v[76:79]
	v_mfma_f32_16x16x32_bf16 v[72:75], v[172:175], v[196:199], v[72:75]
	v_mfma_f32_16x16x32_bf16 v[68:71], v[164:167], v[204:207], v[68:71]
	v_mfma_f32_16x16x32_bf16 v[64:67], v[172:175], v[204:207], v[64:67]
	s_barrier
	s_add_i32 s22, s44, s96
	s_add_i32 m0, s22, 0xffffff80
	ds_read_b128 v[176:179], v143 offset:49152
	ds_read_b128 v[180:183], v143 offset:50176
	ds_read_b128 v[184:187], v143 offset:51200
	ds_read_b128 v[188:191], v143 offset:52224
	ds_read_b128 v[192:195], v143 offset:53248
	ds_read_b128 v[196:199], v143 offset:54272
	ds_read_b128 v[200:203], v143 offset:55296
	ds_read_b128 v[204:207], v143 offset:56320
	global_load_lds_dwordx4 v130, s[90:91] offset:128
	s_add_i32 m0, s22, 0x1f80
	s_add_u32 s22, s90, 0x80080
	s_addc_u32 s23, s91, 0
	s_add_i32 s44, s45, s96
	global_load_lds_dwordx4 v134, s[90:91] offset:128
	s_mov_b32 m0, s44
	s_nop 0
	global_load_lds_dwordx4 v130, s[22:23]
	s_add_i32 m0, s44, 0x2000
	s_nop 0
	global_load_lds_dwordx4 v134, s[22:23]
	s_waitcnt vmcnt(6)
	s_waitcnt lgkmcnt(0)
	s_barrier
	v_mfma_f32_16x16x32_bf16 v[60:63], v[144:147], v[176:179], v[60:63]
	v_mfma_f32_16x16x32_bf16 v[56:59], v[152:155], v[176:179], v[56:59]
	s_add_i32 s43, s43, 2
	v_mfma_f32_16x16x32_bf16 v[52:55], v[144:147], v[184:187], v[52:55]
	s_add_u32 s88, s88, 0x100
	s_addc_u32 s89, s89, 0
	v_mfma_f32_16x16x32_bf16 v[48:51], v[152:155], v[184:187], v[48:51]
	s_add_u32 s41, s41, 0x100
	s_addc_u32 s42, s42, 0
	v_mfma_f32_16x16x32_bf16 v[36:39], v[144:147], v[192:195], v[36:39]
	s_add_u32 s22, s88, 0xfff80080
	s_addc_u32 s23, s89, -1
	v_mfma_f32_16x16x32_bf16 v[32:35], v[152:155], v[192:195], v[32:35]
	s_add_u32 s44, s88, 0xfff80000
	s_addc_u32 s45, s89, -1
	v_mfma_f32_16x16x32_bf16 v[20:23], v[144:147], v[200:203], v[20:23]
	s_cmp_eq_u32 s43, 28
	s_cselect_b32 s23, s30, s23
	s_cselect_b32 s22, s31, s22
	s_cselect_b32 s91, s38, s42
	s_cselect_b32 s90, s39, s41
	v_mfma_f32_16x16x32_bf16 v[16:19], v[152:155], v[200:203], v[16:19]
	s_add_i32 s81, 0, 0x14000
	v_mfma_f32_16x16x32_bf16 v[60:63], v[148:151], v[180:183], v[60:63]
	v_mfma_f32_16x16x32_bf16 v[56:59], v[156:159], v[180:183], v[56:59]
	v_mfma_f32_16x16x32_bf16 v[52:55], v[148:151], v[188:191], v[52:55]
	v_mfma_f32_16x16x32_bf16 v[48:51], v[156:159], v[188:191], v[48:51]
	v_mfma_f32_16x16x32_bf16 v[36:39], v[148:151], v[196:199], v[36:39]
	v_mfma_f32_16x16x32_bf16 v[32:35], v[156:159], v[196:199], v[32:35]
	v_mfma_f32_16x16x32_bf16 v[20:23], v[148:151], v[204:207], v[20:23]
	v_mfma_f32_16x16x32_bf16 v[16:19], v[156:159], v[204:207], v[16:19]
	v_mfma_f32_16x16x32_bf16 v[44:47], v[160:163], v[176:179], v[44:47]
	v_mfma_f32_16x16x32_bf16 v[40:43], v[168:171], v[176:179], v[40:43]
	v_mfma_f32_16x16x32_bf16 v[28:31], v[160:163], v[184:187], v[28:31]
	v_mfma_f32_16x16x32_bf16 v[24:27], v[168:171], v[184:187], v[24:27]
	v_mfma_f32_16x16x32_bf16 v[12:15], v[160:163], v[192:195], v[12:15]
	v_mfma_f32_16x16x32_bf16 v[8:11], v[168:171], v[192:195], v[8:11]
	v_mfma_f32_16x16x32_bf16 v[4:7], v[160:163], v[200:203], v[4:7]
	v_mfma_f32_16x16x32_bf16 v[0:3], v[168:171], v[200:203], v[0:3]
	v_mfma_f32_16x16x32_bf16 v[44:47], v[164:167], v[180:183], v[44:47]
	v_mfma_f32_16x16x32_bf16 v[40:43], v[172:175], v[180:183], v[40:43]
	v_mfma_f32_16x16x32_bf16 v[28:31], v[164:167], v[188:191], v[28:31]
	v_mfma_f32_16x16x32_bf16 v[24:27], v[172:175], v[188:191], v[24:27]
	v_mfma_f32_16x16x32_bf16 v[12:15], v[164:167], v[196:199], v[12:15]
	v_mfma_f32_16x16x32_bf16 v[8:11], v[172:175], v[196:199], v[8:11]
	v_mfma_f32_16x16x32_bf16 v[4:7], v[164:167], v[204:207], v[4:7]
	v_mfma_f32_16x16x32_bf16 v[0:3], v[172:175], v[204:207], v[0:3]
	s_barrier
	s_cmp_gt_u32 s43, 29
	s_cbranch_scc0 .LBB0_631
	s_cmp_eq_u32 s40, 0
	s_cselect_b64 s[30:31], -1, 0
	s_cmp_lg_u32 s40, 0
	s_mov_b64 s[38:39], -1
	s_cbranch_scc0 .LBB0_634
	s_lshl_b32 s22, s80, 8
	s_or_b32 s22, s22, s53
	s_ashr_i32 s22, s22, 6
	s_mov_b64 s[38:39], 0
